# MLA: first four transposed V reads of each P.V cluster issued in the hazard padding before the row-max reduction (s_nop 10 -> 4 ds_read + s_nop 6), size neutral; on top of v162
# speedup vs baseline: 1.0055x; 1.0055x over previous
.LBB0_360:
	ds_read_b64_tr_b16 v[182:183], v2 offset:53248
	ds_read_b64_tr_b16 v[184:185], v2 offset:53760
	ds_read_b64_tr_b16 v[186:187], v2 offset:54272
	ds_read_b64_tr_b16 v[188:189], v2 offset:54784
	s_nop 6
	v_max3_f32 v0, v81, v97, v82
	v_max3_f32 v0, v0, v98, v80
	v_max3_f32 v0, v0, v96, v83
	v_max3_f32 v0, v0, v99, v84
	v_max3_f32 v0, v0, v100, v85
	v_max3_f32 v0, v0, v101, v86
	v_max3_f32 v0, v0, v102, v87
	v_max3_f32 v0, v0, v103, v88
	v_max3_f32 v0, v0, v104, v89
	v_max3_f32 v0, v0, v105, v90
	v_max3_f32 v0, v0, v106, v91
	v_max3_f32 v0, v0, v107, v92
	v_max3_f32 v0, v0, v108, v93
	v_max3_f32 v0, v0, v109, v94
	v_max3_f32 v0, v0, v110, v95
	v_max_f32_e32 v0, v0, v111
	s_cmp_eq_u32 s57, 0
	s_cselect_b64 s[10:11], -1, 0
	s_cmp_lg_u32 s57, 0
	s_cbranch_scc0 .LBB0_368
	v_cmp_lt_f32_e32 vcc, s85, v0
	s_cmp_lg_u64 vcc, 0
	s_cselect_b64 s[36:37], -1, 0
	s_cbranch_execz .LBB0_369
	s_branch .LBB0_370

.LBB0_365:
	ds_read_b64_tr_b16 v[182:183], v2 offset:61440
	ds_read_b64_tr_b16 v[184:185], v2 offset:61952
	ds_read_b64_tr_b16 v[186:187], v2 offset:62464
	ds_read_b64_tr_b16 v[188:189], v2 offset:62976
	s_nop 6
	v_max3_f32 v0, v81, v97, v82
	v_max3_f32 v0, v0, v98, v80
	v_max3_f32 v0, v0, v96, v83
	v_max3_f32 v0, v0, v99, v84
	v_max3_f32 v0, v0, v100, v85
	v_max3_f32 v0, v0, v101, v86
	v_max3_f32 v0, v0, v102, v87
	v_max3_f32 v0, v0, v103, v88
	v_max3_f32 v0, v0, v104, v89
	v_max3_f32 v0, v0, v105, v90
	v_max3_f32 v0, v0, v106, v91
	v_max3_f32 v0, v0, v107, v92
	v_max3_f32 v0, v0, v108, v93
	v_max3_f32 v0, v0, v109, v94
	v_max3_f32 v0, v0, v110, v95
	v_max_f32_e64 v0, v0, v111
	v_cmp_lt_f32_e32 vcc, s85, v0
	s_cbranch_vccz .LBB0_367
	ds_bpermute_b32 v3, v178, v0
	s_waitcnt lgkmcnt(0)
	v_max3_f32 v0, v0, v3, 0
	v_exp_f32_e64 v4, -v0
	v_add_f32_e32 v165, v165, v0
	v_xor_b32_e32 v64, 0x80000000, v165
	v_pk_add_f32 v[80:81], v[80:81], v[0:1] op_sel_hi:[1,0] neg_lo:[0,1] neg_hi:[0,1]
	v_pk_add_f32 v[96:97], v[96:97], v[0:1] op_sel_hi:[1,0] neg_lo:[0,1] neg_hi:[0,1]
	v_pk_add_f32 v[82:83], v[82:83], v[0:1] op_sel_hi:[1,0] neg_lo:[0,1] neg_hi:[0,1]
	v_pk_add_f32 v[98:99], v[98:99], v[0:1] op_sel_hi:[1,0] neg_lo:[0,1] neg_hi:[0,1]
	v_pk_add_f32 v[84:85], v[84:85], v[0:1] op_sel_hi:[1,0] neg_lo:[0,1] neg_hi:[0,1]
	v_pk_add_f32 v[100:101], v[100:101], v[0:1] op_sel_hi:[1,0] neg_lo:[0,1] neg_hi:[0,1]
	v_pk_add_f32 v[86:87], v[86:87], v[0:1] op_sel_hi:[1,0] neg_lo:[0,1] neg_hi:[0,1]
	v_pk_add_f32 v[102:103], v[102:103], v[0:1] op_sel_hi:[1,0] neg_lo:[0,1] neg_hi:[0,1]
	v_pk_add_f32 v[88:89], v[88:89], v[0:1] op_sel_hi:[1,0] neg_lo:[0,1] neg_hi:[0,1]
	v_pk_add_f32 v[104:105], v[104:105], v[0:1] op_sel_hi:[1,0] neg_lo:[0,1] neg_hi:[0,1]
	v_pk_add_f32 v[90:91], v[90:91], v[0:1] op_sel_hi:[1,0] neg_lo:[0,1] neg_hi:[0,1]
	v_pk_add_f32 v[106:107], v[106:107], v[0:1] op_sel_hi:[1,0] neg_lo:[0,1] neg_hi:[0,1]
	v_pk_add_f32 v[92:93], v[92:93], v[0:1] op_sel_hi:[1,0] neg_lo:[0,1] neg_hi:[0,1]
	v_pk_add_f32 v[108:109], v[108:109], v[0:1] op_sel_hi:[1,0] neg_lo:[0,1] neg_hi:[0,1]
	v_pk_add_f32 v[94:95], v[94:95], v[0:1] op_sel_hi:[1,0] neg_lo:[0,1] neg_hi:[0,1]
	v_pk_add_f32 v[110:111], v[110:111], v[0:1] op_sel_hi:[1,0] neg_lo:[0,1] neg_hi:[0,1]
	v_pk_mul_f32 v[62:63], v[62:63], v[4:5] op_sel_hi:[1,0]
	v_pk_mul_f32 v[60:61], v[60:61], v[4:5] op_sel_hi:[1,0]
	v_pk_mul_f32 v[58:59], v[58:59], v[4:5] op_sel_hi:[1,0]
	v_pk_mul_f32 v[56:57], v[56:57], v[4:5] op_sel_hi:[1,0]
	v_pk_mul_f32 v[54:55], v[54:55], v[4:5] op_sel_hi:[1,0]
	v_pk_mul_f32 v[52:53], v[52:53], v[4:5] op_sel_hi:[1,0]
	v_pk_mul_f32 v[50:51], v[50:51], v[4:5] op_sel_hi:[1,0]
	v_pk_mul_f32 v[48:49], v[48:49], v[4:5] op_sel_hi:[1,0]
	v_pk_mul_f32 v[46:47], v[46:47], v[4:5] op_sel_hi:[1,0]
	v_pk_mul_f32 v[44:45], v[44:45], v[4:5] op_sel_hi:[1,0]
	v_pk_mul_f32 v[42:43], v[42:43], v[4:5] op_sel_hi:[1,0]
	v_pk_mul_f32 v[40:41], v[40:41], v[4:5] op_sel_hi:[1,0]
	v_pk_mul_f32 v[38:39], v[38:39], v[4:5] op_sel_hi:[1,0]
	v_pk_mul_f32 v[36:37], v[36:37], v[4:5] op_sel_hi:[1,0]
	v_pk_mul_f32 v[34:35], v[34:35], v[4:5] op_sel_hi:[1,0]
	v_pk_mul_f32 v[32:33], v[32:33], v[4:5] op_sel_hi:[1,0]
	v_mov_b32_e32 v65, v64
	v_mov_b32_e32 v66, v64
	v_mov_b32_e32 v67, v64
	v_mov_b32_e32 v68, v64
	v_mov_b32_e32 v69, v64
	v_mov_b32_e32 v70, v64
	v_mov_b32_e32 v71, v64
	v_mov_b32_e32 v72, v64
	v_mov_b32_e32 v73, v64
	v_mov_b32_e32 v74, v64
	v_mov_b32_e32 v75, v64
	v_mov_b32_e32 v76, v64
	v_mov_b32_e32 v77, v64
	v_mov_b32_e32 v78, v64
	v_mov_b32_e32 v79, v64
	v_mul_f32_e32 v6, v6, v4
.LBB0_367:
	v_exp_f32_e32 v3, v80
	v_exp_f32_e32 v7, v96
	v_exp_f32_e32 v0, v81
	v_exp_f32_e32 v4, v97
	v_exp_f32_e32 v17, v98
	v_add_f32_e32 v5, v7, v3
	v_exp_f32_e32 v14, v99
	v_pk_add_f32 v[8:9], v[4:5], v[0:1]
	v_exp_f32_e32 v5, v82
	v_pk_add_f32 v[10:11], v[8:9], v[8:9] op_sel_hi:[0,1]
	v_exp_f32_e32 v10, v83
	v_exp_f32_e32 v18, v101
	v_add_f32_e32 v15, v17, v5
	v_exp_f32_e32 v22, v103
	v_pk_add_f32 v[8:9], v[14:15], v[10:11]
	v_exp_f32_e32 v11, v84
	v_pk_add_f32 v[12:13], v[8:9], v[8:9] op_sel_hi:[0,1]
	v_exp_f32_e32 v15, v100
	v_exp_f32_e32 v12, v85
	v_exp_f32_e32 v26, v105
	v_exp_f32_e32 v30, v107
	v_add_f32_e32 v19, v15, v11
	v_pk_add_f32 v[8:9], v[18:19], v[12:13]
	v_exp_f32_e32 v13, v86
	v_pk_add_f32 v[20:21], v[8:9], v[8:9] op_sel_hi:[0,1]
	v_exp_f32_e32 v19, v102
	v_exp_f32_e32 v20, v87
	v_exp_f32_e32 v82, v109
	v_add_f32_e32 v23, v19, v13
	v_pk_add_f32 v[8:9], v[22:23], v[20:21]
	v_exp_f32_e32 v21, v88
	v_pk_add_f32 v[24:25], v[8:9], v[8:9] op_sel_hi:[0,1]
	v_exp_f32_e32 v23, v104
	v_exp_f32_e32 v24, v89
	v_add_f32_e32 v27, v23, v21
	v_pk_add_f32 v[8:9], v[26:27], v[24:25]
	v_exp_f32_e32 v25, v90
	v_pk_add_f32 v[28:29], v[8:9], v[8:9] op_sel_hi:[0,1]
	v_exp_f32_e32 v27, v106
	v_exp_f32_e32 v28, v91
	v_exp_f32_e32 v91, v94
	v_exp_f32_e32 v90, v111
	v_add_f32_e32 v31, v27, v25
	v_pk_add_f32 v[8:9], v[30:31], v[28:29]
	v_exp_f32_e32 v29, v92
	v_pk_add_f32 v[80:81], v[8:9], v[8:9] op_sel_hi:[0,1]
	v_exp_f32_e32 v31, v108
	v_exp_f32_e32 v80, v93
	v_exp_f32_e32 v92, v110
	v_add_f32_e32 v83, v31, v29
	v_pk_add_f32 v[8:9], v[82:83], v[80:81]
	s_nop 0
	v_pk_add_f32 v[88:89], v[8:9], v[8:9] op_sel_hi:[0,1]
	v_exp_f32_e32 v88, v95
	v_cvt_pk_bf16_f32 v8, v3, v0
	v_cvt_pk_bf16_f32 v9, v5, v10
	v_cvt_pk_bf16_f32 v10, v11, v12
	v_cvt_pk_bf16_f32 v11, v13, v20
	v_cvt_pk_bf16_f32 v12, v7, v4
	v_cvt_pk_bf16_f32 v13, v17, v14
	v_cvt_pk_bf16_f32 v14, v15, v18
	v_cvt_pk_bf16_f32 v15, v19, v22
	v_cvt_pk_bf16_f32 v18, v21, v24
	v_cvt_pk_bf16_f32 v19, v25, v28
	v_cvt_pk_bf16_f32 v20, v29, v80
	v_cvt_pk_bf16_f32 v21, v91, v88
	v_cvt_pk_bf16_f32 v22, v23, v26
	v_cvt_pk_bf16_f32 v23, v27, v30
	v_cvt_pk_bf16_f32 v24, v31, v82
	v_cvt_pk_bf16_f32 v25, v92, v90
	v_add_u32_e32 v0, 0xd000, v2
	s_waitcnt lgkmcnt(2)
	v_mfma_f32_32x32x16_bf16 v[48:63], v[182:185], v[8:11], v[48:63]
	ds_read_b64_tr_b16 v[26:27], v0 offset:12288
	ds_read_b64_tr_b16 v[28:29], v0 offset:12800
	ds_read_b64_tr_b16 v[84:85], v0 offset:13312
	ds_read_b64_tr_b16 v[86:87], v0 offset:13824
	v_add_f32_e32 v91, v92, v91
	s_waitcnt lgkmcnt(2)
	v_mfma_f32_32x32x16_bf16 v[32:47], v[26:29], v[8:11], v[32:47]
	v_mfma_f32_32x32x16_bf16 v[48:63], v[186:189], v[18:21], v[48:63]
	s_waitcnt lgkmcnt(0)
	v_mfma_f32_32x32x16_bf16 v[32:47], v[84:87], v[18:21], v[32:47]
	ds_read_b64_tr_b16 v[8:9], v2 offset:63488
	ds_read_b64_tr_b16 v[10:11], v2 offset:64000
	ds_read_b64_tr_b16 v[18:19], v2 offset:64512
	ds_read_b64_tr_b16 v[20:21], v2 offset:65024
	s_waitcnt lgkmcnt(2)
	v_mfma_f32_32x32x16_bf16 v[48:63], v[8:11], v[12:15], v[48:63]
	ds_read_b64_tr_b16 v[2:3], v0 offset:14336
	ds_read_b64_tr_b16 v[4:5], v0 offset:14848
	ds_read_b64_tr_b16 v[8:9], v0 offset:15360
	ds_read_b64_tr_b16 v[10:11], v0 offset:15872
	s_waitcnt lgkmcnt(2)
	v_mfma_f32_32x32x16_bf16 v[32:47], v[2:5], v[12:15], v[32:47]
	v_add_f32_e64 v2, v90, v88
	v_add_f32_e64 v3, v91, v89
	v_add_f32_e32 v0, v2, v3
	v_add_f32_e32 v6, v6, v0
	v_mfma_f32_32x32x16_bf16 v[48:63], v[18:21], v[22:25], v[48:63]
	s_waitcnt lgkmcnt(0)
	v_mfma_f32_32x32x16_bf16 v[32:47], v[8:11], v[22:25], v[32:47]
	s_andn2_b64 vcc, exec, s[4:5]
	s_cbranch_vccnz .LBB0_350
	s_branch .LBB0_374

.LBB0_372:
	v_exp_f32_e32 v7, v80
	v_exp_f32_e32 v17, v96
	v_exp_f32_e32 v0, v81
	v_exp_f32_e32 v4, v97
	v_exp_f32_e32 v96, v98
	v_add_f32_e32 v5, v17, v7
	v_exp_f32_e32 v14, v99
	v_pk_add_f32 v[8:9], v[4:5], v[0:1]
	v_exp_f32_e32 v5, v82
	v_pk_add_f32 v[10:11], v[8:9], v[8:9] op_sel_hi:[0,1]
	v_exp_f32_e32 v10, v83
	v_exp_f32_e32 v18, v101
	v_add_f32_e32 v15, v96, v5
	v_exp_f32_e32 v22, v103
	v_pk_add_f32 v[8:9], v[14:15], v[10:11]
	v_exp_f32_e32 v11, v84
	v_pk_add_f32 v[12:13], v[8:9], v[8:9] op_sel_hi:[0,1]
	v_exp_f32_e32 v15, v100
	v_exp_f32_e32 v12, v85
	v_exp_f32_e32 v26, v105
	v_exp_f32_e32 v30, v107
	v_add_f32_e32 v19, v15, v11
	v_pk_add_f32 v[8:9], v[18:19], v[12:13]
	v_exp_f32_e32 v13, v86
	v_pk_add_f32 v[20:21], v[8:9], v[8:9] op_sel_hi:[0,1]
	v_exp_f32_e32 v19, v102
	v_exp_f32_e32 v20, v87
	v_exp_f32_e32 v82, v109
	v_add_f32_e32 v23, v19, v13
	v_pk_add_f32 v[8:9], v[22:23], v[20:21]
	v_exp_f32_e32 v21, v88
	v_pk_add_f32 v[24:25], v[8:9], v[8:9] op_sel_hi:[0,1]
	v_exp_f32_e32 v23, v104
	v_exp_f32_e32 v24, v89
	v_add_f32_e32 v27, v23, v21
	v_pk_add_f32 v[8:9], v[26:27], v[24:25]
	v_exp_f32_e32 v25, v90
	v_pk_add_f32 v[28:29], v[8:9], v[8:9] op_sel_hi:[0,1]
	v_exp_f32_e32 v27, v106
	v_exp_f32_e32 v28, v91
	v_exp_f32_e32 v91, v94
	v_exp_f32_e32 v90, v111
	v_add_f32_e32 v31, v27, v25
	v_pk_add_f32 v[8:9], v[30:31], v[28:29]
	v_exp_f32_e32 v29, v92
	v_pk_add_f32 v[80:81], v[8:9], v[8:9] op_sel_hi:[0,1]
	v_exp_f32_e32 v31, v108
	v_exp_f32_e32 v80, v93
	v_exp_f32_e32 v92, v110
	v_add_f32_e32 v83, v31, v29
	v_pk_add_f32 v[8:9], v[82:83], v[80:81]
	s_nop 0
	v_pk_add_f32 v[88:89], v[8:9], v[8:9] op_sel_hi:[0,1]
	v_exp_f32_e32 v88, v95
	v_cvt_pk_bf16_f32 v8, v7, v0
	v_cvt_pk_bf16_f32 v9, v5, v10
	v_cvt_pk_bf16_f32 v10, v11, v12
	v_cvt_pk_bf16_f32 v11, v13, v20
	v_cvt_pk_bf16_f32 v12, v17, v4
	v_cvt_pk_bf16_f32 v13, v96, v14
	v_cvt_pk_bf16_f32 v14, v15, v18
	v_cvt_pk_bf16_f32 v15, v19, v22
	v_cvt_pk_bf16_f32 v18, v21, v24
	v_cvt_pk_bf16_f32 v19, v25, v28
	v_cvt_pk_bf16_f32 v20, v29, v80
	v_cvt_pk_bf16_f32 v21, v91, v88
	v_cvt_pk_bf16_f32 v22, v23, v26
	v_cvt_pk_bf16_f32 v23, v27, v30
	v_cvt_pk_bf16_f32 v24, v31, v82
	v_cvt_pk_bf16_f32 v25, v92, v90
	s_waitcnt lgkmcnt(2)
	v_mfma_f32_32x32x16_bf16 v[48:63], v[182:185], v[8:11], v[48:63]
	ds_read_b64_tr_b16 v[26:27], v2 offset:57344
	ds_read_b64_tr_b16 v[28:29], v2 offset:57856
	ds_read_b64_tr_b16 v[84:85], v2 offset:58368
	ds_read_b64_tr_b16 v[86:87], v2 offset:58880
	v_add_f32_e32 v91, v92, v91
	v_pk_add_f32 v[4:5], v[90:91], v[88:89]
	s_nop 0
	v_add_f32_e32 v0, v4, v5
	v_add_f32_e32 v6, v6, v0
	s_waitcnt lgkmcnt(2)
	v_mfma_f32_32x32x16_bf16 v[32:47], v[26:29], v[8:11], v[32:47]
	v_mfma_f32_32x32x16_bf16 v[48:63], v[186:189], v[18:21], v[48:63]
	s_waitcnt lgkmcnt(0)
	v_mfma_f32_32x32x16_bf16 v[32:47], v[84:87], v[18:21], v[32:47]
	ds_read_b64_tr_b16 v[8:9], v2 offset:55296
	ds_read_b64_tr_b16 v[10:11], v2 offset:55808
	ds_read_b64_tr_b16 v[18:19], v2 offset:56320
	ds_read_b64_tr_b16 v[20:21], v2 offset:56832
	s_waitcnt lgkmcnt(2)
	v_mfma_f32_32x32x16_bf16 v[48:63], v[8:11], v[12:15], v[48:63]
	ds_read_b64_tr_b16 v[8:9], v2 offset:59392
	ds_read_b64_tr_b16 v[10:11], v2 offset:59904
	ds_read_b64_tr_b16 v[26:27], v2 offset:60416
	ds_read_b64_tr_b16 v[28:29], v2 offset:60928
	s_waitcnt lgkmcnt(2)
	v_mfma_f32_32x32x16_bf16 v[32:47], v[8:11], v[12:15], v[32:47]
	v_mfma_f32_32x32x16_bf16 v[48:63], v[18:21], v[22:25], v[48:63]
	s_waitcnt lgkmcnt(0)
	v_mfma_f32_32x32x16_bf16 v[32:47], v[26:29], v[22:25], v[32:47]
	s_add_i32 s2, s57, 64
	s_cmp_gt_i32 s2, s54
	s_cbranch_scc0 .LBB0_363

.LBB0_398:
	ds_read_b64_tr_b16 v[182:183], v2 offset:53248
	ds_read_b64_tr_b16 v[184:185], v2 offset:53760
	ds_read_b64_tr_b16 v[186:187], v2 offset:54272
	ds_read_b64_tr_b16 v[188:189], v2 offset:54784
	s_nop 6
	v_max3_f32 v0, v81, v97, v82
	v_max3_f32 v0, v0, v98, v80
	v_max3_f32 v0, v0, v96, v83
	v_max3_f32 v0, v0, v99, v84
	v_max3_f32 v0, v0, v100, v85
	v_max3_f32 v0, v0, v101, v86
	v_max3_f32 v0, v0, v102, v87
	v_max3_f32 v0, v0, v103, v88
	v_max3_f32 v0, v0, v104, v89
	v_max3_f32 v0, v0, v105, v90
	v_max3_f32 v0, v0, v106, v91
	v_max3_f32 v0, v0, v107, v92
	v_max3_f32 v0, v0, v108, v93
	v_max3_f32 v0, v0, v109, v94
	v_max3_f32 v0, v0, v110, v95
	v_max_f32_e32 v0, v0, v111
	s_cmp_eq_u32 s37, 0
	s_cselect_b64 s[10:11], -1, 0
	s_cmp_lg_u32 s37, 0
	s_cbranch_scc0 .LBB0_406
	v_cmp_lt_f32_e32 vcc, s85, v0
	s_cmp_lg_u64 vcc, 0
	s_cselect_b64 s[16:17], -1, 0
	s_cbranch_execz .LBB0_407
	s_branch .LBB0_408

.LBB0_410:
	v_exp_f32_e32 v7, v80
	v_exp_f32_e32 v17, v96
	v_exp_f32_e32 v0, v81
	v_exp_f32_e32 v4, v97
	v_exp_f32_e32 v96, v98
	v_add_f32_e32 v5, v17, v7
	v_exp_f32_e32 v14, v99
	v_pk_add_f32 v[8:9], v[4:5], v[0:1]
	v_exp_f32_e32 v5, v82
	v_pk_add_f32 v[10:11], v[8:9], v[8:9] op_sel_hi:[0,1]
	v_exp_f32_e32 v10, v83
	v_exp_f32_e32 v18, v101
	v_add_f32_e32 v15, v96, v5
	v_exp_f32_e32 v22, v103
	v_pk_add_f32 v[8:9], v[14:15], v[10:11]
	v_exp_f32_e32 v11, v84
	v_pk_add_f32 v[12:13], v[8:9], v[8:9] op_sel_hi:[0,1]
	v_exp_f32_e32 v15, v100
	v_exp_f32_e32 v12, v85
	v_exp_f32_e32 v26, v105
	v_exp_f32_e32 v30, v107
	v_add_f32_e32 v19, v15, v11
	v_pk_add_f32 v[8:9], v[18:19], v[12:13]
	v_exp_f32_e32 v13, v86
	v_pk_add_f32 v[20:21], v[8:9], v[8:9] op_sel_hi:[0,1]
	v_exp_f32_e32 v19, v102
	v_exp_f32_e32 v20, v87
	v_exp_f32_e32 v82, v109
	v_add_f32_e32 v23, v19, v13
	v_pk_add_f32 v[8:9], v[22:23], v[20:21]
	v_exp_f32_e32 v21, v88
	v_pk_add_f32 v[24:25], v[8:9], v[8:9] op_sel_hi:[0,1]
	v_exp_f32_e32 v23, v104
	v_exp_f32_e32 v24, v89
	v_add_f32_e32 v27, v23, v21
	v_pk_add_f32 v[8:9], v[26:27], v[24:25]
	v_exp_f32_e32 v25, v90
	v_pk_add_f32 v[28:29], v[8:9], v[8:9] op_sel_hi:[0,1]
	v_exp_f32_e32 v27, v106
	v_exp_f32_e32 v28, v91
	v_exp_f32_e32 v91, v94
	v_exp_f32_e32 v90, v111
	v_add_f32_e32 v31, v27, v25
	v_pk_add_f32 v[8:9], v[30:31], v[28:29]
	v_exp_f32_e32 v29, v92
	v_pk_add_f32 v[80:81], v[8:9], v[8:9] op_sel_hi:[0,1]
	v_exp_f32_e32 v31, v108
	v_exp_f32_e32 v80, v93
	v_exp_f32_e32 v92, v110
	v_add_f32_e32 v83, v31, v29
	v_pk_add_f32 v[8:9], v[82:83], v[80:81]
	s_nop 0
	v_pk_add_f32 v[88:89], v[8:9], v[8:9] op_sel_hi:[0,1]
	v_exp_f32_e32 v88, v95
	v_cvt_pk_bf16_f32 v8, v7, v0
	v_cvt_pk_bf16_f32 v9, v5, v10
	v_cvt_pk_bf16_f32 v10, v11, v12
	v_cvt_pk_bf16_f32 v11, v13, v20
	v_cvt_pk_bf16_f32 v12, v17, v4
	v_cvt_pk_bf16_f32 v13, v96, v14
	v_cvt_pk_bf16_f32 v14, v15, v18
	v_cvt_pk_bf16_f32 v15, v19, v22
	v_cvt_pk_bf16_f32 v18, v21, v24
	v_cvt_pk_bf16_f32 v19, v25, v28
	v_cvt_pk_bf16_f32 v20, v29, v80
	v_cvt_pk_bf16_f32 v21, v91, v88
	v_cvt_pk_bf16_f32 v22, v23, v26
	v_cvt_pk_bf16_f32 v23, v27, v30
	v_cvt_pk_bf16_f32 v24, v31, v82
	v_cvt_pk_bf16_f32 v25, v92, v90
	s_waitcnt lgkmcnt(2)
	v_mfma_f32_32x32x16_bf16 v[48:63], v[182:185], v[8:11], v[48:63]
	ds_read_b64_tr_b16 v[26:27], v2 offset:57344
	ds_read_b64_tr_b16 v[28:29], v2 offset:57856
	ds_read_b64_tr_b16 v[84:85], v2 offset:58368
	ds_read_b64_tr_b16 v[86:87], v2 offset:58880
	v_add_f32_e32 v91, v92, v91
	v_pk_add_f32 v[4:5], v[90:91], v[88:89]
	s_nop 0
	v_add_f32_e32 v0, v4, v5
	v_add_f32_e32 v6, v6, v0
	s_waitcnt lgkmcnt(2)
	v_mfma_f32_32x32x16_bf16 v[32:47], v[26:29], v[8:11], v[32:47]
	v_mfma_f32_32x32x16_bf16 v[48:63], v[186:189], v[18:21], v[48:63]
	s_waitcnt lgkmcnt(0)
	v_mfma_f32_32x32x16_bf16 v[32:47], v[84:87], v[18:21], v[32:47]
	ds_read_b64_tr_b16 v[8:9], v2 offset:55296
	ds_read_b64_tr_b16 v[10:11], v2 offset:55808
	ds_read_b64_tr_b16 v[18:19], v2 offset:56320
	ds_read_b64_tr_b16 v[20:21], v2 offset:56832
	s_waitcnt lgkmcnt(2)
	v_mfma_f32_32x32x16_bf16 v[48:63], v[8:11], v[12:15], v[48:63]
	ds_read_b64_tr_b16 v[8:9], v2 offset:59392
	ds_read_b64_tr_b16 v[10:11], v2 offset:59904
	ds_read_b64_tr_b16 v[26:27], v2 offset:60416
	ds_read_b64_tr_b16 v[28:29], v2 offset:60928
	s_waitcnt lgkmcnt(2)
	v_mfma_f32_32x32x16_bf16 v[32:47], v[8:11], v[12:15], v[32:47]
	v_mfma_f32_32x32x16_bf16 v[48:63], v[18:21], v[22:25], v[48:63]
	s_waitcnt lgkmcnt(0)
	v_mfma_f32_32x32x16_bf16 v[32:47], v[26:29], v[22:25], v[32:47]
	s_add_i32 s2, s37, 64
	s_cmp_gt_i32 s2, s28
	s_cbranch_scc0 .LBB0_401
